# norm loop software prefetch (next 2 rows loaded one iteration ahead) + removed cg grid.sync before first XCD barrier
# speedup vs baseline: 1.0107x; 1.0107x over previous
; #define GRID_BAR() do { XcdBarrier b_; b_.bar = (unsigned*)args_ptr()->ws; b_.x = xb_xcc_id(); b_.st = (volatile LAS unsigned*)(lds + 131072 + 320) + 8; xcd_barrier(b_); } while (0)
; __global__ void __launch_bounds__(NTHREADS, 2) fwd_kernel(Args a_unused) {
;     ...
;     grid.sync();
;     GRID_BAR();
.LBB0_41:
	v_lshrrev_b32_e32 v1, 20, v0
	v_lshrrev_b32_e32 v0, 10, v0
	v_or_b32_e32 v0, v0, v1
	s_movk_i32 s1, 0x3ff
	v_and_or_b32 v0, v0, s1, v143
	v_cmp_eq_u32_e32 vcc, 0, v0
	s_barrier
	s_mov_b64 s[6:7], exec

; __device__ __forceinline__ unsigned cvt_pk_bf16(float lo, float hi) { f32x2_t v = {lo, hi}; bf16x2_t b = __builtin_convertvector(v, bf16x2_t); return __builtin_bit_cast(unsigned, b); }
; template <bool HB, bool FINAL>
; __device__ __forceinline__ void norm_rows(const void* src, const bf16* y, float ys, bf16* hdst, const float* gain, bf16* xn, float* fout, float* fstage, int gw, int NGW, int lane) {
;     ...
;     for (int m0 = gw; m0 < T; m0 += 2 * NGW) {
;         f32x4 v[2][4]; u32x2 yw[2][4];
; #pragma unroll
;         for (int r = 0; r < 2; ++r) { const int m = m0 + r * NGW;
;             if (HB) { const u32x2* hr = (const u32x2*)((const bf16*)src + (size_t)m * D) + lane;
; #pragma unroll
;                 for (int j = 0; j < 4; ++j) { const u32x2 w = hr[64 * j]; v[r][j] = (f32x4){__uint_as_float(w.x << 16), __uint_as_float(w.x & 0xffff0000u), __uint_as_float(w.y << 16), __uint_as_float(w.y & 0xffff0000u)}; }
;             } else { const f32x4* xr = (const f32x4*)((const float*)src + (size_t)m * D) + lane;
; #pragma unroll
;                 for (int j = 0; j < 4; ++j) v[r][j] = xr[64 * j]; }
;             if (y) { const u32x2* yr = (const u32x2*)(y + (size_t)m * D) + lane;
; #pragma unroll
;                 for (int j = 0; j < 4; ++j) yw[r][j] = yr[64 * j]; } }
;     ...
;         for (int r = 0; r < 2; ++r) { const int m = m0 + r * NGW; const float rstd = rsqrtf(s[r] * (1.f / D) + EPS);
;             if (!FINAL && hdst) { u32x2* hr = (u32x2*)(hdst + (size_t)m * D) + lane;
; #pragma unroll
;                 for (int j = 0; j < 4; ++j) { u32x2 w; w.x = cvt_pk_bf16(v[r][j].x, v[r][j].y); w.y = cvt_pk_bf16(v[r][j].z, v[r][j].w); hr[64 * j] = w; } }
;             if (FINAL) { f32x4* o = (f32x4*)((m >= T / 2 ? fout : fstage) + (size_t)m * D) + lane;
; #pragma unroll
;                 for (int j = 0; j < 4; ++j) o[64 * j] = v[r][j] * rstd * gv[j];
;             } else { u32x2* o = (u32x2*)(xn + (size_t)m * D) + lane;
; #pragma unroll
;                 for (int j = 0; j < 4; ++j) { const f32x4 q = v[r][j] * rstd * gv[j]; u32x2 w; w.x = cvt_pk_bf16(q.x, q.y); w.y = cvt_pk_bf16(q.z, q.w); o[64 * j] = w; } } }
.LBB0_254:
	s_waitcnt lgkmcnt(0)
	v_add_f32_e32 v26, v48, v49
	v_fmamk_f32 v26, v26, 0x3a800000, v142
	v_mul_f32_e32 v27, 0x4b800000, v26
	v_cmp_gt_f32_e32 vcc, s72, v26
	s_add_i32 s6, s12, s33
	s_cmpk_gt_i32 s6, 0x7fff
	v_cndmask_b32_e32 v26, v26, v27, vcc
	v_rsq_f32_e32 v28, v26
	v_lshl_add_u64 v[26:27], v[22:23], 0, s[14:15]
	v_mul_f32_e32 v29, 0x45800000, v28
	v_cndmask_b32_e32 v28, v28, v29, vcc
	v_pk_mul_f32 v[30:31], v[60:61], v[28:29] op_sel_hi:[1,0]
	v_pk_mul_f32 v[32:33], v[54:55], v[28:29] op_sel_hi:[1,0]
	v_pk_mul_f32 v[30:31], v[2:3], v[30:31]
	v_pk_mul_f32 v[32:33], v[4:5], v[32:33]
	v_cvt_pk_bf16_f32 v30, v30, v31
	v_cvt_pk_bf16_f32 v31, v32, v33
	global_store_dwordx2 v[26:27], v[30:31], off
	v_pk_mul_f32 v[30:31], v[58:59], v[28:29] op_sel_hi:[1,0]
	v_pk_mul_f32 v[32:33], v[50:51], v[28:29] op_sel_hi:[1,0]
	v_pk_mul_f32 v[30:31], v[6:7], v[30:31]
	v_pk_mul_f32 v[32:33], v[8:9], v[32:33]
	v_cvt_pk_bf16_f32 v30, v30, v31
	v_cvt_pk_bf16_f32 v31, v32, v33
	global_store_dwordx2 v[26:27], v[30:31], off offset:512
	v_pk_mul_f32 v[30:31], v[56:57], v[28:29] op_sel_hi:[1,0]
	v_pk_mul_f32 v[32:33], v[46:47], v[28:29] op_sel_hi:[1,0]
	v_pk_mul_f32 v[30:31], v[10:11], v[30:31]
	v_pk_mul_f32 v[32:33], v[12:13], v[32:33]
	v_cvt_pk_bf16_f32 v30, v30, v31
	v_cvt_pk_bf16_f32 v31, v32, v33
	global_store_dwordx2 v[26:27], v[30:31], off offset:1024
	v_pk_mul_f32 v[30:31], v[52:53], v[28:29] op_sel_hi:[1,0]
	v_pk_mul_f32 v[28:29], v[44:45], v[28:29] op_sel_hi:[1,0]
	v_pk_mul_f32 v[30:31], v[14:15], v[30:31]
	v_pk_mul_f32 v[28:29], v[16:17], v[28:29]
	v_cvt_pk_bf16_f32 v30, v30, v31
	v_cvt_pk_bf16_f32 v31, v28, v29
	global_store_dwordx2 v[26:27], v[30:31], off offset:1536
	s_cbranch_scc1 .LBB0_259
	s_cmp_lg_u64 s[10:11], 0
	s_cbranch_scc1 .LN_w16
	s_waitcnt vmcnt(8)
	s_branch .LN_copy
.LN_w16:
	s_waitcnt vmcnt(16)
	s_branch .LN_copy
.LBB0_255:
	s_ashr_i32 s7, s6, 31
	s_lshl_b64 s[16:17], s[6:7], 11
	v_lshl_add_u64 v[26:27], v[18:19], 0, s[16:17]
	global_load_dwordx2 v[86:87], v[26:27], off
	global_load_dwordx2 v[88:89], v[26:27], off offset:512
	global_load_dwordx2 v[90:91], v[26:27], off offset:1024
	global_load_dwordx2 v[92:93], v[26:27], off offset:1536
	v_lshl_add_u64 v[26:27], v[20:21], 0, s[16:17]
	global_load_dwordx2 v[94:95], v[26:27], off
	global_load_dwordx2 v[96:97], v[26:27], off offset:512
	global_load_dwordx2 v[98:99], v[26:27], off offset:1024
	global_load_dwordx2 v[100:101], v[26:27], off offset:1536
	s_add_i32 s12, s6, s33
	s_ashr_i32 s13, s12, 31
	s_lshl_b64 s[14:15], s[12:13], 11
	v_lshl_add_u64 v[26:27], v[18:19], 0, s[14:15]
	global_load_dwordx2 v[102:103], v[26:27], off
	global_load_dwordx2 v[104:105], v[26:27], off offset:512
	global_load_dwordx2 v[106:107], v[26:27], off offset:1024
	global_load_dwordx2 v[108:109], v[26:27], off offset:1536
	v_lshl_add_u64 v[26:27], v[20:21], 0, s[14:15]
	global_load_dwordx2 v[110:111], v[26:27], off
	global_load_dwordx2 v[112:113], v[26:27], off offset:512
	global_load_dwordx2 v[114:115], v[26:27], off offset:1024
	global_load_dwordx2 v[116:117], v[26:27], off offset:1536
	s_waitcnt vmcnt(0)
.LN_copy:
	v_mov_b32_e32 v28, v86
	v_mov_b32_e32 v29, v87
	v_mov_b32_e32 v32, v88
	v_mov_b32_e32 v33, v89
	v_mov_b32_e32 v38, v90
	v_mov_b32_e32 v39, v91
	v_mov_b32_e32 v42, v92
	v_mov_b32_e32 v43, v93
	v_mov_b32_e32 v30, v94
	v_mov_b32_e32 v31, v95
	v_mov_b32_e32 v36, v96
	v_mov_b32_e32 v37, v97
	v_mov_b32_e32 v40, v98
	v_mov_b32_e32 v41, v99
	v_mov_b32_e32 v60, v100
	v_mov_b32_e32 v61, v101
	v_mov_b32_e32 v54, v102
	v_mov_b32_e32 v55, v103
	v_mov_b32_e32 v50, v104
	v_mov_b32_e32 v51, v105
	v_mov_b32_e32 v46, v106
	v_mov_b32_e32 v47, v107
	v_mov_b32_e32 v44, v108
	v_mov_b32_e32 v45, v109
	v_mov_b32_e32 v58, v110
	v_mov_b32_e32 v59, v111
	v_mov_b32_e32 v56, v112
	v_mov_b32_e32 v57, v113
	v_mov_b32_e32 v52, v114
	v_mov_b32_e32 v53, v115
	v_mov_b32_e32 v48, v116
	v_mov_b32_e32 v49, v117
	s_ashr_i32 s7, s6, 31
	s_lshl_b64 s[16:17], s[6:7], 11
	s_add_i32 s12, s6, s33
	s_ashr_i32 s13, s12, 31
	s_lshl_b64 s[14:15], s[12:13], 11
	s_add_i32 s22, s12, s33
	s_cmpk_gt_i32 s22, 0x7fff
	s_cbranch_scc1 .LN_C
	s_ashr_i32 s23, s22, 31
	s_lshl_b64 s[18:19], s[22:23], 11
	s_add_i32 s22, s22, s33
	s_ashr_i32 s23, s22, 31
	s_lshl_b64 s[20:21], s[22:23], 11
	v_lshl_add_u64 v[118:119], v[18:19], 0, s[18:19]
	global_load_dwordx2 v[86:87], v[118:119], off
	global_load_dwordx2 v[88:89], v[118:119], off offset:512
	global_load_dwordx2 v[90:91], v[118:119], off offset:1024
	global_load_dwordx2 v[92:93], v[118:119], off offset:1536
	v_lshl_add_u64 v[118:119], v[20:21], 0, s[18:19]
	global_load_dwordx2 v[94:95], v[118:119], off
	global_load_dwordx2 v[96:97], v[118:119], off offset:512
	global_load_dwordx2 v[98:99], v[118:119], off offset:1024
	global_load_dwordx2 v[100:101], v[118:119], off offset:1536
	v_lshl_add_u64 v[118:119], v[18:19], 0, s[20:21]
	global_load_dwordx2 v[102:103], v[118:119], off
	global_load_dwordx2 v[104:105], v[118:119], off offset:512
	global_load_dwordx2 v[106:107], v[118:119], off offset:1024
	global_load_dwordx2 v[108:109], v[118:119], off offset:1536
	v_lshl_add_u64 v[118:119], v[20:21], 0, s[20:21]
	global_load_dwordx2 v[110:111], v[118:119], off
	global_load_dwordx2 v[112:113], v[118:119], off offset:512
	global_load_dwordx2 v[114:115], v[118:119], off offset:1024
	global_load_dwordx2 v[116:117], v[118:119], off offset:1536
; __device__ __forceinline__ unsigned cvt_pk_bf16(float lo, float hi) { f32x2_t v = {lo, hi}; bf16x2_t b = __builtin_convertvector(v, bf16x2_t); return __builtin_bit_cast(unsigned, b); }
; template <bool HB, bool FINAL>
; __device__ __forceinline__ void norm_rows(const void* src, const bf16* y, float ys, bf16* hdst, const float* gain, bf16* xn, float* fout, float* fstage, int gw, int NGW, int lane) {
;     ...
;         float s[2];
; #pragma unroll
;         for (int r = 0; r < 2; ++r) { s[r] = 0.f;
;             if (y) {
; #pragma unroll
;                 for (int j = 0; j < 4; ++j) { const u32x2 w = yw[r][j];
;                     v[r][j].x += ys * __uint_as_float(w.x << 16); v[r][j].y += ys * __uint_as_float(w.x & 0xffff0000u); v[r][j].z += ys * __uint_as_float(w.y << 16); v[r][j].w += ys * __uint_as_float(w.y & 0xffff0000u); } }
; #pragma unroll
;             for (int j = 0; j < 4; ++j) s[r] += (v[r][j].x * v[r][j].x + v[r][j].y * v[r][j].y) + (v[r][j].z * v[r][j].z + v[r][j].w * v[r][j].w); }
; #pragma unroll
;         for (int o = 1; o < 64; o <<= 1) { s[0] += __shfl_xor(s[0], o); s[1] += __shfl_xor(s[1], o); }
; #pragma unroll
;         for (int r = 0; r < 2; ++r) { const int m = m0 + r * NGW; const float rstd = rsqrtf(s[r] * (1.f / D) + EPS);
;             if (!FINAL && hdst) { u32x2* hr = (u32x2*)(hdst + (size_t)m * D) + lane;
; #pragma unroll
;                 for (int j = 0; j < 4; ++j) { u32x2 w; w.x = cvt_pk_bf16(v[r][j].x, v[r][j].y); w.y = cvt_pk_bf16(v[r][j].z, v[r][j].w); hr[64 * j] = w; } }
.LN_C:
	s_andn2_b64 vcc, exec, s[10:11]
	v_lshlrev_b32_e32 v26, 16, v28
	v_and_b32_e32 v27, 0xffff0000, v28
	v_lshlrev_b32_e32 v70, 16, v30
	v_and_b32_e32 v71, 0xffff0000, v30
	v_lshlrev_b32_e32 v28, 16, v29
	v_and_b32_e32 v29, 0xffff0000, v29
	v_lshlrev_b32_e32 v30, 16, v31
	v_and_b32_e32 v31, 0xffff0000, v31
	v_pk_fma_f32 v[26:27], v[34:35], v[70:71], v[26:27]
	v_pk_fma_f32 v[28:29], v[34:35], v[30:31], v[28:29]
	v_lshlrev_b32_e32 v30, 16, v32
	v_and_b32_e32 v31, 0xffff0000, v32
	v_lshlrev_b32_e32 v70, 16, v36
	v_and_b32_e32 v71, 0xffff0000, v36
	v_lshlrev_b32_e32 v32, 16, v33
	v_and_b32_e32 v33, 0xffff0000, v33
	v_lshlrev_b32_e32 v36, 16, v37
	v_and_b32_e32 v37, 0xffff0000, v37
	v_pk_fma_f32 v[30:31], v[34:35], v[70:71], v[30:31]
	v_pk_fma_f32 v[32:33], v[34:35], v[36:37], v[32:33]
	v_lshlrev_b32_e32 v36, 16, v38
	v_and_b32_e32 v37, 0xffff0000, v38
	v_lshlrev_b32_e32 v70, 16, v40
	v_and_b32_e32 v71, 0xffff0000, v40
	v_lshlrev_b32_e32 v38, 16, v39
	v_and_b32_e32 v39, 0xffff0000, v39
	v_lshlrev_b32_e32 v40, 16, v41
	v_and_b32_e32 v41, 0xffff0000, v41
	v_pk_fma_f32 v[36:37], v[34:35], v[70:71], v[36:37]
	v_pk_fma_f32 v[38:39], v[34:35], v[40:41], v[38:39]
	v_lshlrev_b32_e32 v40, 16, v42
	v_and_b32_e32 v41, 0xffff0000, v42
	v_lshlrev_b32_e32 v70, 16, v60
	v_and_b32_e32 v71, 0xffff0000, v60
	v_pk_fma_f32 v[40:41], v[34:35], v[70:71], v[40:41]
	v_lshlrev_b32_e32 v42, 16, v43
	v_and_b32_e32 v43, 0xffff0000, v43
	v_lshlrev_b32_e32 v60, 16, v61
	v_and_b32_e32 v61, 0xffff0000, v61
	v_mov_b32_e32 v70, v27
	v_mov_b32_e32 v71, v29
	v_pk_fma_f32 v[42:43], v[34:35], v[60:61], v[42:43]
	v_mov_b32_e32 v60, v26
	v_mov_b32_e32 v61, v28
	v_pk_mul_f32 v[70:71], v[70:71], v[70:71]
	v_mov_b32_e32 v72, v31
	v_mov_b32_e32 v73, v33
	v_pk_fma_f32 v[60:61], v[60:61], v[60:61], v[70:71]
	v_mov_b32_e32 v70, v30
	v_mov_b32_e32 v71, v32
	v_pk_mul_f32 v[72:73], v[72:73], v[72:73]
	v_mul_f32_e32 v74, v39, v39
	v_pk_fma_f32 v[70:71], v[70:71], v[70:71], v[72:73]
	v_mul_f32_e32 v72, v37, v37
	v_pk_add_f32 v[60:61], v[60:61], v[60:61] op_sel:[0,1] op_sel_hi:[1,0]
	v_pk_add_f32 v[70:71], v[70:71], v[70:71] op_sel:[0,1] op_sel_hi:[1,0]
	v_pk_fma_f32 v[72:73], v[36:37], v[36:37], v[72:73] op_sel_hi:[1,1,0]
	v_pk_fma_f32 v[74:75], v[38:39], v[38:39], v[74:75] op_sel_hi:[1,1,0]
	v_pk_mul_f32 v[76:77], v[40:41], v[40:41]
	v_pk_mul_f32 v[78:79], v[42:43], v[42:43]
	v_mov_b32_e32 v61, v76
	v_mov_b32_e32 v71, v77
	v_mov_b32_e32 v73, v78
	v_mov_b32_e32 v75, v79
	v_pk_add_f32 v[60:61], v[60:61], v[70:71]
	v_pk_add_f32 v[70:71], v[72:73], v[74:75]
	s_nop 0
	v_pk_add_f32 v[60:61], v[60:61], v[70:71]
	v_lshlrev_b32_e32 v70, 16, v58
	v_add_f32_e32 v69, v60, v61
	v_lshlrev_b32_e32 v60, 16, v54
	v_and_b32_e32 v61, 0xffff0000, v54
	v_and_b32_e32 v71, 0xffff0000, v58
	v_lshlrev_b32_e32 v54, 16, v55
	v_and_b32_e32 v55, 0xffff0000, v55
	v_lshlrev_b32_e32 v58, 16, v59
	v_and_b32_e32 v59, 0xffff0000, v59
	v_pk_fma_f32 v[60:61], v[34:35], v[70:71], v[60:61]
	v_pk_fma_f32 v[54:55], v[34:35], v[58:59], v[54:55]
	v_lshlrev_b32_e32 v58, 16, v50
	v_and_b32_e32 v59, 0xffff0000, v50
	v_lshlrev_b32_e32 v70, 16, v56
	v_and_b32_e32 v71, 0xffff0000, v56
	v_lshlrev_b32_e32 v50, 16, v51
	v_and_b32_e32 v51, 0xffff0000, v51
	v_lshlrev_b32_e32 v56, 16, v57
	v_and_b32_e32 v57, 0xffff0000, v57
	v_pk_fma_f32 v[58:59], v[34:35], v[70:71], v[58:59]
	v_pk_fma_f32 v[50:51], v[34:35], v[56:57], v[50:51]
	v_lshlrev_b32_e32 v56, 16, v46
	v_and_b32_e32 v57, 0xffff0000, v46
	v_lshlrev_b32_e32 v70, 16, v52
	v_and_b32_e32 v71, 0xffff0000, v52
	v_lshlrev_b32_e32 v46, 16, v47
	v_and_b32_e32 v47, 0xffff0000, v47
	v_lshlrev_b32_e32 v52, 16, v53
	v_and_b32_e32 v53, 0xffff0000, v53
	v_pk_fma_f32 v[56:57], v[34:35], v[70:71], v[56:57]
	v_pk_fma_f32 v[46:47], v[34:35], v[52:53], v[46:47]
	v_lshlrev_b32_e32 v52, 16, v44
	v_and_b32_e32 v53, 0xffff0000, v44
	v_lshlrev_b32_e32 v70, 16, v48
	v_and_b32_e32 v71, 0xffff0000, v48
	v_lshlrev_b32_e32 v44, 16, v45
	v_and_b32_e32 v45, 0xffff0000, v45
	v_lshlrev_b32_e32 v48, 16, v49
	v_and_b32_e32 v49, 0xffff0000, v49
	v_pk_fma_f32 v[52:53], v[34:35], v[70:71], v[52:53]
	v_pk_fma_f32 v[44:45], v[34:35], v[48:49], v[44:45]
	v_pk_mul_f32 v[48:49], v[60:61], v[60:61]
	v_pk_mul_f32 v[70:71], v[54:55], v[54:55]
	v_pk_mul_f32 v[72:73], v[58:59], v[58:59]
	v_pk_mul_f32 v[74:75], v[50:51], v[50:51]
	v_pk_mul_f32 v[76:77], v[56:57], v[56:57]
	v_pk_mul_f32 v[78:79], v[46:47], v[46:47]
	v_add_f32_e32 v74, v74, v75
	v_add_f32_e32 v72, v72, v73
	v_add_f32_e32 v70, v70, v71
	v_add_f32_e32 v48, v48, v49
	v_add_f32_e32 v72, v72, v74
	v_add_f32_e32 v48, v48, v70
	v_add_f32_e32 v49, v78, v79
	v_add_f32_e32 v70, v76, v77
	v_pk_mul_f32 v[80:81], v[52:53], v[52:53]
	v_pk_mul_f32 v[82:83], v[44:45], v[44:45]
	v_add_f32_e32 v48, v48, v72
	v_add_f32_e32 v49, v70, v49
	v_add_f32_e32 v48, v48, v49
	v_add_f32_e32 v49, v82, v83
	v_add_f32_e32 v70, v80, v81
	v_add_f32_e32 v49, v70, v49
	v_add_f32_e32 v48, v48, v49
	ds_bpermute_b32 v49, v62, v69
	v_cndmask_b32_e64 v71, 0, 1, s[10:11]
	v_cmp_ne_u32_e64 s[6:7], 1, v71
	s_waitcnt lgkmcnt(0)
	v_add_f32_e32 v49, v69, v49
	ds_bpermute_b32 v69, v62, v48
	s_waitcnt lgkmcnt(0)
	v_add_f32_e32 v48, v48, v69
	ds_bpermute_b32 v69, v63, v49
	s_waitcnt lgkmcnt(0)
	v_add_f32_e32 v49, v49, v69
	ds_bpermute_b32 v69, v63, v48
	s_waitcnt lgkmcnt(0)
	v_add_f32_e32 v48, v48, v69
	ds_bpermute_b32 v69, v64, v49
	s_waitcnt lgkmcnt(0)
	v_add_f32_e32 v49, v49, v69
	ds_bpermute_b32 v69, v64, v48
	s_waitcnt lgkmcnt(0)
	v_add_f32_e32 v48, v48, v69
	ds_bpermute_b32 v69, v65, v49
	s_waitcnt lgkmcnt(0)
	v_add_f32_e32 v49, v49, v69
	ds_bpermute_b32 v69, v65, v48
	s_waitcnt lgkmcnt(0)
	v_add_f32_e32 v48, v48, v69
	ds_bpermute_b32 v69, v66, v49
	s_waitcnt lgkmcnt(0)
	v_add_f32_e32 v69, v49, v69
	ds_bpermute_b32 v49, v66, v48
	ds_bpermute_b32 v70, v67, v69
	s_waitcnt lgkmcnt(1)
	v_add_f32_e32 v48, v48, v49
	ds_bpermute_b32 v49, v67, v48
	s_cbranch_vccnz .LBB0_257
	v_lshl_add_u64 v[72:73], v[24:25], 0, s[16:17]
	v_cvt_pk_bf16_f32 v74, v26, v27
	v_cvt_pk_bf16_f32 v75, v28, v29
	global_store_dwordx2 v[72:73], v[74:75], off
	v_cvt_pk_bf16_f32 v74, v30, v31
	v_cvt_pk_bf16_f32 v75, v32, v33
	global_store_dwordx2 v[72:73], v[74:75], off offset:512
	v_cvt_pk_bf16_f32 v74, v36, v37
	v_cvt_pk_bf16_f32 v75, v38, v39
	global_store_dwordx2 v[72:73], v[74:75], off offset:1024
	v_cvt_pk_bf16_f32 v74, v40, v41
	v_cvt_pk_bf16_f32 v75, v42, v43
	global_store_dwordx2 v[72:73], v[74:75], off offset:1536
